# pool GEMM prologue: removed the full vmcnt(0) wait in the middle of its LDS-DMA issue sequence (it guarded the compiler's pooling loads, replaced earlier by the hand-written pooling)
# baseline (speedup 1.0000x reference)
.LBB0_603:
	v_mov_b32_e32 v2, s9
	s_waitcnt vmcnt(0)
	s_barrier
	ds_read_b64 v[0:1], v2
	s_ashr_i32 s65, s64, 31
	s_lshl_b64 s[4:5], s[64:65], 1
	s_add_u32 s8, s6, s4
	v_mov_b32_e32 v34, v252
	s_waitcnt lgkmcnt(0)
	v_readfirstlane_b32 s48, v0
	ds_read_b64 v[0:1], v2
	s_addc_u32 s47, s7, s5
	s_ashr_i32 s63, s62, 31
	s_lshl_b64 s[0:1], s[62:63], 17
	s_waitcnt lgkmcnt(0)
	v_lshlrev_b32_e32 v0, 4, v34
	v_readfirstlane_b32 s63, v1
	v_add_u32_e32 v1, 0x2000, v0
	v_ashrrev_i32_e32 v2, 31, v1
	v_lshrrev_b32_e32 v2, 22, v2
	v_add_u32_e32 v2, v1, v2
	v_ashrrev_i32_e32 v2, 10, v2
	v_mul_i32_i24_e32 v4, 0x400, v2
	v_sub_u32_e32 v1, v1, v4
	v_lshrrev_b32_e32 v4, 4, v1
	v_bitop3_b32 v1, v4, v1, 32 bitop3:0x6c
	v_ashrrev_i32_e32 v4, 31, v1
	v_lshrrev_b32_e32 v4, 26, v4
	v_add_u32_e32 v4, v1, v4
	v_lshlrev_b32_e32 v3, 5, v2
	v_ashrrev_i32_e32 v5, 6, v4
	v_and_b32_e32 v4, 0xc0, v4
	v_lshlrev_b32_e32 v2, 3, v2
	v_sub_u32_e32 v1, v1, v4
	v_mov_b32_e32 v6, 1
	v_and_b32_e32 v2, -16, v2
	v_and_b32_e32 v3, 32, v3
	v_ashrrev_i16_sdwa v1, v6, sext(v1) dst_sel:DWORD dst_unused:UNUSED_PAD src0_sel:DWORD src1_sel:BYTE_0
	v_add_u32_e32 v2, v5, v2
	v_add_u32_sdwa v1, v3, sext(v1) dst_sel:DWORD dst_unused:UNUSED_PAD src0_sel:DWORD src1_sel:WORD_0
	v_lshlrev_b32_e32 v3, 9, v2
	v_lshl_add_u32 v32, v1, 1, v3
	v_bfe_i32 v3, v34, 27, 1
	v_lshrrev_b32_e32 v3, 22, v3
	v_add_u32_e32 v3, v0, v3
	v_and_b32_e32 v3, 0xfffffc00, v3
	v_sub_u32_e32 v0, v0, v3
	v_lshrrev_b32_e32 v3, 4, v0
	v_ashrrev_i32_e32 v1, 31, v34
	v_bitop3_b32 v3, v3, v0, 32 bitop3:0x6c
	v_ashrrev_i32_e32 v0, 31, v0
	v_lshrrev_b32_e32 v1, 26, v1
	v_lshrrev_b32_e32 v0, 26, v0
	v_add_u32_e32 v1, v34, v1
	v_add_u32_e32 v0, v3, v0
	v_ashrrev_i32_e32 v1, 6, v1
	v_ashrrev_i32_e32 v0, 6, v0
	s_add_u32 s66, s79, s0
	v_readfirstlane_b32 s88, v34
	v_mad_u64_u32 v[8:9], s[14:15], v2, s16, v[32:33]
	v_lshlrev_b32_e32 v2, 5, v1
	v_mul_i32_i24_e32 v4, 64, v0
	v_lshlrev_b32_e32 v1, 3, v1
	s_addc_u32 s67, s80, s1
	s_ashr_i32 s0, s88, 6
	v_sub_u32_e32 v3, v3, v4
	v_and_b32_e32 v1, -16, v1
	s_lshl_b32 s68, s0, 10
	v_and_b32_e32 v2, 32, v2
	v_ashrrev_i16_sdwa v3, v6, sext(v3) dst_sel:DWORD dst_unused:UNUSED_PAD src0_sel:DWORD src1_sel:BYTE_0
	v_add_u32_e32 v0, v0, v1
	v_add_u32_sdwa v2, v2, sext(v3) dst_sel:DWORD dst_unused:UNUSED_PAD src0_sel:DWORD src1_sel:WORD_0
	v_lshlrev_b32_e32 v1, 9, v0
	s_add_i32 s62, s68, 0
	v_lshl_add_u32 v144, v2, 1, v1
	s_add_i32 m0, s62, 0x10000
	s_ashr_i32 s46, s88, 8
	v_mad_u64_u32 v[26:27], s[14:15], v0, s16, v[144:145]
	s_lshl_b32 s1, s39, 19
	global_load_lds_dwordx4 v144, s[66:67]
	s_add_i32 m0, s62, 0x12000
	s_add_u32 s14, s66, 0x10000
	global_load_lds_dwordx4 v32, s[66:67]
	s_addc_u32 s15, s67, 0
	s_add_i32 m0, s62, 0x14000
	v_mov_b32_e32 v33, v145
	global_load_lds_dwordx4 v144, s[14:15]
	s_add_i32 m0, s62, 0x16000
	s_add_u32 s70, s8, s1
	s_addc_u32 s71, s47, 0
	s_add_i32 s8, s62, 0x2000
	v_lshl_add_u64 v[10:11], s[14:15], 0, v[144:145]
	v_lshl_add_u64 v[12:13], s[14:15], 0, v[32:33]
	global_load_lds_dwordx4 v32, s[14:15]
	s_mov_b32 m0, s62
	s_add_u32 s14, s70, 0x40000
	global_load_lds_dwordx4 v26, s[70:71]
	s_mov_b32 m0, s8
	s_addc_u32 s15, s71, 0
	s_add_i32 vcc_lo, s62, 0x4000
	global_load_lds_dwordx4 v8, s[70:71]
	s_mov_b32 m0, vcc_lo
	s_add_i32 vcc_hi, s62, 0x6000
	global_load_lds_dwordx4 v26, s[14:15]
	s_mov_b32 m0, vcc_hi
	v_mov_b32_e32 v27, v145
	global_load_lds_dwordx4 v8, s[14:15]
	v_mov_b32_e32 v9, v145
	v_lshl_add_u64 v[0:1], s[66:67], 0, v[144:145]
	v_lshl_add_u64 v[2:3], s[66:67], 0, v[32:33]
	v_lshl_add_u64 v[14:15], s[70:71], 0, v[26:27]
	v_lshl_add_u64 v[24:25], s[70:71], 0, v[8:9]
	v_lshl_add_u64 v[4:5], s[14:15], 0, v[26:27]
	v_lshl_add_u64 v[6:7], s[14:15], 0, v[8:9]
	s_cmp_lg_u32 s46, 1
	s_cbranch_scc1 .LBB0_605
	s_barrier
